# GEMM start stagger: delayed half selected by bit 4 of the workgroup id (pairs of adjacent XCD slots stay in phase) instead of bit 3
# speedup vs baseline: 1.0171x; 1.0037x over previous
; __global__ void __launch_bounds__(NWAVES * 64, 2) hymba_fwd(Args A) {
;     ...
;     {
;         pg8::Gemm g{(const pg8::bf16_t*)(ws + WS_XA), (const pg8::bf16_t*)(ws + WS_W1), M1, DIN, DM, DM};
;         pg8::StaticOrder S; S.init(M1, DIN, G, bx);
;         pg8::Epi1 E{(const float*)(ws + WS_RS1), (const float*)(ws + WS_ROPE), A.out, (pg8::bf16_t*)(ws + WS_QD), (pg8::bf16_t*)(ws + WS_QS), (pg8::bf16_t*)(ws + WS_KD), (pg8::bf16_t*)(ws + WS_KS),
;                     (pg8::bf16_t*)(ws + WS_VDT), (pg8::bf16_t*)(ws + WS_VST)};
;         pg8::gemm_phase<pg8::Epi1, pg8::StaticOrder, true, true>(lds, g, S, E);
.LBB0_102:
	s_or_b64 exec, exec, s[0:1]
	s_barrier
	s_cmp_lt_u32 s22, 36
	s_cbranch_scc1 .Lstag_p1
	s_bitcmp1_b32 s22, 4
	s_cbranch_scc0 .Lstag_p1
	s_sleep 127
	s_sleep 127
	s_sleep 127

; __global__ void __launch_bounds__(NWAVES * 64, 2) hymba_fwd(Args A) {
;     ...
;     xcd_barrier(bar);
;     {
;         pg8::Gemm g{(const pg8::bf16_t*)(ws + WS_X1B), (const pg8::bf16_t*)(ws + WS_W3), M2, DFF, DM, DM};
;         pg8::StaticOrder S; S.init(M2, DFF, G, bx);
;         pg8::Epi3 E{(const float*)(ws + WS_SS2), (pg8::bf16_t*)(ws + WS_H)};
;         pg8::gemm_phase<pg8::Epi3, pg8::StaticOrder, true, true>(lds, g, S, E);
.LBB0_746:
	s_or_b64 exec, exec, s[0:1]
	v_mov_b32_e32 v9, v138
	s_waitcnt lgkmcnt(0)
	s_barrier
	s_cmp_lt_u32 s22, 32
	s_cbranch_scc1 .Lstag_p4
	s_bitcmp1_b32 s22, 4
	s_cbranch_scc0 .Lstag_p4
	s_sleep 127
	s_sleep 127
	s_sleep 127
